# PB gate-tile epilogue: dropped 14 per-group vmcnt(0) waits that only drained the previous store (bias loads already waited in the first group)
# baseline (speedup 1.0000x reference)
; #define GAS __attribute__((address_space(1)))
; DI unsigned pk2(float lo, float hi) { f32x2 v = {lo, hi}; bf16x2_t r = __builtin_convertvector(v, bf16x2_t); return __builtin_bit_cast(unsigned, r); }
; DI float sigmoidf_(float x) { return __builtin_amdgcn_rcpf(1.f + __expf(-x)); }
;     DI bool operator()(AccT& acc, const Unit& u, int wr, int wc, int fr, int fq) const {
;     ...
;         for (int bj = 0; bj < 2; ++bj) {
;             const int col = col0 + bj * HALF; const bool gate = (col >= ZC_GATE) && (col < ZC_VRES); const bool s5c = col < S5W;
;             f32x4 b0 = {0.f, 0.f, 0.f, 0.f}, b1 = b0;
;             if (gate) { b0 = *(const GAS f32x4*)(gbias + (col - ZC_GATE)); b1 = *(const GAS f32x4*)(gbias + (col - ZC_GATE) + 4); }
; #pragma unroll
;             for (int ai = 0; ai < 2; ++ai)
; #pragma unroll
;                 for (int m = 0; m < 4; ++m) {
;                     f32x4 v0 = acc[ai][bj][m][0] * rsv[ai][m], v1 = acc[ai][bj][m][1] * rsv[ai][m];
;                     if (gate) { v0 += b0; v1 += b1;
; #pragma unroll
;                         for (int e = 0; e < 4; ++e) { v0[e] = sigmoidf_(v0[e]); v1[e] = sigmoidf_(v1[e]); } }
;                     u32x4 w; w.x = pk2(v0[0], v0[1]); w.y = pk2(v0[2], v0[3]); w.z = pk2(v1[0], v1[1]); w.w = pk2(v1[2], v1[3]);
;                     if (s5c) *(GAS u32x4*)(ZS5 + ((size_t)(col >> 4) * M + (row0 + ai * HALF + m * 16)) * 16 + (col & 8)) = w;
;                     else *(GAS u32x4*)(Z + (size_t)(row0 + ai * HALF + m * 16) * ZP + col) = w;
;                 }
.LBB0_385:
	s_or_b64 exec, exec, s[16:17]
	s_movk_i32 s0, 0x2ff
	v_cmp_lt_i32_e32 vcc, s0, v184
	v_ashrrev_i32_e32 v159, 31, v158
	s_and_saveexec_b64 s[0:1], vcc
	s_xor_b64 s[0:1], exec, s[0:1]
	v_mov_b64_e32 v[128:129], s[6:7]
	s_movk_i32 s16, 0x5a00
	v_mad_i64_i32 v[128:129], s[16:17], v158, s16, v[128:129]
	v_lshl_add_u64 v[168:169], v[184:185], 1, v[128:129]
	s_or_saveexec_b64 s[0:1], s[0:1]
	v_ashrrev_i32_e32 v128, 4, v184
	v_ashrrev_i32_e32 v129, 31, v128
	v_lshlrev_b64 v[128:129], 19, v[128:129]
	v_lshl_add_u64 v[132:133], s[10:11], 0, v[128:129]
	v_lshlrev_b64 v[130:131], 5, v[158:159]
	v_lshlrev_b32_e32 v128, 1, v144
	s_xor_b64 exec, exec, s[0:1]
	v_lshl_add_u64 v[168:169], v[132:133], 0, v[130:131]
	v_mov_b32_e32 v129, v185
	v_lshl_add_u64 v[168:169], v[168:169], 0, v[128:129]
	s_or_b64 exec, exec, s[0:1]
	v_cvt_pk_bf16_f32 v175, v164, v165
	v_mov_b32_e32 v164, v157
	v_cvt_pk_bf16_f32 v174, v134, v135
	v_cvt_pk_bf16_f32 v176, v162, v163
	v_cvt_pk_bf16_f32 v177, v166, v167
	v_pk_mul_f32 v[134:135], v[126:127], v[164:165] op_sel_hi:[1,0]
	v_pk_mul_f32 v[124:125], v[124:125], v[164:165] op_sel_hi:[1,0]
	v_pk_mul_f32 v[162:163], v[122:123], v[164:165] op_sel_hi:[1,0]
	v_pk_mul_f32 v[126:127], v[120:121], v[164:165] op_sel_hi:[1,0]
	global_store_dwordx4 v[168:169], v[174:177], off
	s_and_saveexec_b64 s[0:1], s[4:5]
	s_xor_b64 s[0:1], exec, s[0:1]
	s_andn2_saveexec_b64 s[16:17], s[0:1]
	s_cbranch_execz .LBB0_391
	v_pk_add_f32 v[122:123], v[124:125], v[104:105]
	v_pk_add_f32 v[124:125], v[126:127], v[108:109]
	v_mul_f32_e32 v122, 0xbfb8aa3b, v122
	v_exp_f32_e32 v122, v122
	v_mul_f32_e32 v124, 0xbfb8aa3b, v124
	v_exp_f32_e32 v126, v124
	v_mul_f32_e32 v123, 0xbfb8aa3b, v123
	v_exp_f32_e32 v123, v123
	v_mul_f32_e32 v125, 0xbfb8aa3b, v125
	v_exp_f32_e32 v127, v125
	v_pk_add_f32 v[120:121], v[134:135], v[106:107]
	v_add_f32_e32 v122, 1.0, v122
	v_pk_add_f32 v[134:135], v[162:163], v[110:111]
	v_rcp_f32_e32 v124, v122
	v_add_f32_e32 v122, 1.0, v126
	v_mul_f32_e32 v120, 0xbfb8aa3b, v120
	v_rcp_f32_e32 v126, v122
	v_add_f32_e32 v122, 1.0, v123
	v_exp_f32_e32 v120, v120
	v_mul_f32_e32 v123, 0xbfb8aa3b, v134
	v_rcp_f32_e32 v125, v122
	v_add_f32_e32 v122, 1.0, v127
	v_exp_f32_e32 v123, v123
	v_mul_f32_e32 v121, 0xbfb8aa3b, v121
	v_rcp_f32_e32 v127, v122
	v_exp_f32_e32 v121, v121
	v_mul_f32_e32 v122, 0xbfb8aa3b, v135
	v_exp_f32_e32 v122, v122
	v_add_f32_e32 v120, 1.0, v120
	v_rcp_f32_e32 v134, v120
	v_add_f32_e32 v120, 1.0, v123
	v_rcp_f32_e32 v162, v120
	v_add_f32_e32 v120, 1.0, v121
	v_rcp_f32_e32 v135, v120
	v_add_f32_e32 v120, 1.0, v122
	v_rcp_f32_e32 v163, v120
.LBB0_391:
	s_or_b64 exec, exec, s[16:17]
	v_or_b32_e32 v120, 16, v158
	v_ashrrev_i32_e32 v121, 31, v120
	s_and_saveexec_b64 s[0:1], vcc
	s_xor_b64 s[0:1], exec, s[0:1]
	v_mov_b64_e32 v[122:123], s[6:7]
	s_movk_i32 s16, 0x5a00
	v_mad_i64_i32 v[122:123], s[16:17], v120, s16, v[122:123]
	v_lshl_add_u64 v[164:165], v[184:185], 1, v[122:123]
	s_or_saveexec_b64 s[0:1], s[0:1]
	v_lshlrev_b64 v[122:123], 5, v[120:121]
	s_xor_b64 exec, exec, s[0:1]
	v_lshl_add_u64 v[164:165], v[132:133], 0, v[122:123]
	v_mov_b32_e32 v129, v185
	v_lshl_add_u64 v[164:165], v[164:165], 0, v[128:129]
	s_or_b64 exec, exec, s[0:1]
	v_cvt_pk_bf16_f32 v124, v124, v125
	v_cvt_pk_bf16_f32 v125, v134, v135
	v_cvt_pk_bf16_f32 v126, v126, v127
	v_cvt_pk_bf16_f32 v127, v162, v163
	global_store_dwordx4 v[164:165], v[124:127], off
	v_pk_mul_f32 v[116:117], v[116:117], v[154:155] op_sel_hi:[1,0]
	s_nop 0
	v_pk_mul_f32 v[124:125], v[118:119], v[154:155] op_sel_hi:[1,0]
	v_pk_mul_f32 v[126:127], v[114:115], v[154:155] op_sel_hi:[1,0]
	v_pk_mul_f32 v[118:119], v[112:113], v[154:155] op_sel_hi:[1,0]
	s_and_saveexec_b64 s[0:1], s[4:5]
	s_xor_b64 s[0:1], exec, s[0:1]
	s_andn2_saveexec_b64 s[16:17], s[0:1]
	s_cbranch_execz .LBB0_397
	v_pk_add_f32 v[114:115], v[116:117], v[104:105]
	v_pk_add_f32 v[116:117], v[118:119], v[108:109]
	v_mul_f32_e32 v114, 0xbfb8aa3b, v114
	v_exp_f32_e32 v114, v114
	v_mul_f32_e32 v116, 0xbfb8aa3b, v116
	v_exp_f32_e32 v118, v116
	v_mul_f32_e32 v115, 0xbfb8aa3b, v115
	v_exp_f32_e32 v115, v115
	v_mul_f32_e32 v117, 0xbfb8aa3b, v117
	v_exp_f32_e32 v119, v117
	v_pk_add_f32 v[112:113], v[124:125], v[106:107]
	v_add_f32_e32 v114, 1.0, v114
	v_pk_add_f32 v[124:125], v[126:127], v[110:111]
	v_rcp_f32_e32 v116, v114
	v_add_f32_e32 v114, 1.0, v118
	v_mul_f32_e32 v112, 0xbfb8aa3b, v112
	v_rcp_f32_e32 v118, v114
	v_add_f32_e32 v114, 1.0, v115
	v_exp_f32_e32 v112, v112
	v_mul_f32_e32 v115, 0xbfb8aa3b, v124
	v_rcp_f32_e32 v117, v114
	v_add_f32_e32 v114, 1.0, v119
	v_exp_f32_e32 v115, v115
	v_mul_f32_e32 v113, 0xbfb8aa3b, v113
	v_rcp_f32_e32 v119, v114
	v_exp_f32_e32 v113, v113
	v_mul_f32_e32 v114, 0xbfb8aa3b, v125
	v_exp_f32_e32 v114, v114
	v_add_f32_e32 v112, 1.0, v112
	v_rcp_f32_e32 v124, v112
	v_add_f32_e32 v112, 1.0, v115
	v_rcp_f32_e32 v126, v112
	v_add_f32_e32 v112, 1.0, v113
	v_rcp_f32_e32 v125, v112
	v_add_f32_e32 v112, 1.0, v114
	v_rcp_f32_e32 v127, v112
; #define GAS __attribute__((address_space(1)))
; DI unsigned pk2(float lo, float hi) { f32x2 v = {lo, hi}; bf16x2_t r = __builtin_convertvector(v, bf16x2_t); return __builtin_bit_cast(unsigned, r); }
; DI float sigmoidf_(float x) { return __builtin_amdgcn_rcpf(1.f + __expf(-x)); }
;     DI bool operator()(AccT& acc, const Unit& u, int wr, int wc, int fr, int fq) const {
;     ...
;             for (int ai = 0; ai < 2; ++ai)
; #pragma unroll
;                 for (int m = 0; m < 4; ++m) {
;                     f32x4 v0 = acc[ai][bj][m][0] * rsv[ai][m], v1 = acc[ai][bj][m][1] * rsv[ai][m];
;                     if (gate) { v0 += b0; v1 += b1;
; #pragma unroll
;                         for (int e = 0; e < 4; ++e) { v0[e] = sigmoidf_(v0[e]); v1[e] = sigmoidf_(v1[e]); } }
;                     u32x4 w; w.x = pk2(v0[0], v0[1]); w.y = pk2(v0[2], v0[3]); w.z = pk2(v1[0], v1[1]); w.w = pk2(v1[2], v1[3]);
;                     if (s5c) *(GAS u32x4*)(ZS5 + ((size_t)(col >> 4) * M + (row0 + ai * HALF + m * 16)) * 16 + (col & 8)) = w;
;                     else *(GAS u32x4*)(Z + (size_t)(row0 + ai * HALF + m * 16) * ZP + col) = w;
;                 }
.LBB0_397:
	s_or_b64 exec, exec, s[16:17]
	v_or_b32_e32 v112, 32, v158
	v_ashrrev_i32_e32 v113, 31, v112
	s_and_saveexec_b64 s[0:1], vcc
	s_xor_b64 s[0:1], exec, s[0:1]
	v_mov_b64_e32 v[114:115], s[6:7]
	s_movk_i32 s16, 0x5a00
	v_mad_i64_i32 v[114:115], s[16:17], v112, s16, v[114:115]
	v_lshl_add_u64 v[134:135], v[184:185], 1, v[114:115]
	s_or_saveexec_b64 s[0:1], s[0:1]
	v_lshlrev_b64 v[114:115], 5, v[112:113]
	s_xor_b64 exec, exec, s[0:1]
	v_lshl_add_u64 v[134:135], v[132:133], 0, v[114:115]
	v_mov_b32_e32 v129, v185
	v_lshl_add_u64 v[134:135], v[134:135], 0, v[128:129]
	s_or_b64 exec, exec, s[0:1]
	v_cvt_pk_bf16_f32 v116, v116, v117
	v_cvt_pk_bf16_f32 v117, v124, v125
	v_cvt_pk_bf16_f32 v118, v118, v119
	v_cvt_pk_bf16_f32 v119, v126, v127
	v_mov_b32_e32 v124, v155
	global_store_dwordx4 v[134:135], v[116:119], off
	v_pk_mul_f32 v[100:101], v[100:101], v[124:125] op_sel_hi:[1,0]
	s_nop 0
	v_pk_mul_f32 v[116:117], v[102:103], v[124:125] op_sel_hi:[1,0]
	v_pk_mul_f32 v[118:119], v[98:99], v[124:125] op_sel_hi:[1,0]
	v_pk_mul_f32 v[102:103], v[96:97], v[124:125] op_sel_hi:[1,0]
	s_and_saveexec_b64 s[0:1], s[4:5]
	s_xor_b64 s[0:1], exec, s[0:1]
	s_andn2_saveexec_b64 s[16:17], s[0:1]
	s_cbranch_execz .LBB0_403
	v_pk_add_f32 v[98:99], v[100:101], v[104:105]
	v_pk_add_f32 v[100:101], v[102:103], v[108:109]
	v_mul_f32_e32 v98, 0xbfb8aa3b, v98
	v_exp_f32_e32 v98, v98
	v_mul_f32_e32 v100, 0xbfb8aa3b, v100
	v_exp_f32_e32 v102, v100
	v_mul_f32_e32 v99, 0xbfb8aa3b, v99
	v_exp_f32_e32 v99, v99
	v_mul_f32_e32 v101, 0xbfb8aa3b, v101
	v_exp_f32_e32 v103, v101
	v_pk_add_f32 v[96:97], v[116:117], v[106:107]
	v_add_f32_e32 v98, 1.0, v98
	v_pk_add_f32 v[116:117], v[118:119], v[110:111]
	v_rcp_f32_e32 v100, v98
	v_add_f32_e32 v98, 1.0, v102
	v_mul_f32_e32 v96, 0xbfb8aa3b, v96
	v_rcp_f32_e32 v102, v98
	v_add_f32_e32 v98, 1.0, v99
	v_exp_f32_e32 v96, v96
	v_mul_f32_e32 v99, 0xbfb8aa3b, v116
	v_rcp_f32_e32 v101, v98
	v_add_f32_e32 v98, 1.0, v103
	v_exp_f32_e32 v99, v99
	v_mul_f32_e32 v97, 0xbfb8aa3b, v97
	v_rcp_f32_e32 v103, v98
	v_exp_f32_e32 v97, v97
	v_mul_f32_e32 v98, 0xbfb8aa3b, v117
	v_exp_f32_e32 v98, v98
	v_add_f32_e32 v96, 1.0, v96
	v_rcp_f32_e32 v116, v96
	v_add_f32_e32 v96, 1.0, v99
	v_rcp_f32_e32 v118, v96
	v_add_f32_e32 v96, 1.0, v97
	v_rcp_f32_e32 v117, v96
	v_add_f32_e32 v96, 1.0, v98
	v_rcp_f32_e32 v119, v96
.LBB0_403:
	s_or_b64 exec, exec, s[16:17]
	v_or_b32_e32 v96, 48, v158
	v_ashrrev_i32_e32 v97, 31, v96
	s_and_saveexec_b64 s[0:1], vcc
	s_xor_b64 s[0:1], exec, s[0:1]
	v_mov_b64_e32 v[98:99], s[6:7]
	s_movk_i32 s16, 0x5a00
	v_mad_i64_i32 v[98:99], s[16:17], v96, s16, v[98:99]
	v_lshl_add_u64 v[124:125], v[184:185], 1, v[98:99]
	s_or_saveexec_b64 s[0:1], s[0:1]
	v_lshlrev_b64 v[98:99], 5, v[96:97]
	s_xor_b64 exec, exec, s[0:1]
	v_lshl_add_u64 v[124:125], v[132:133], 0, v[98:99]
	v_mov_b32_e32 v129, v185
	v_lshl_add_u64 v[124:125], v[124:125], 0, v[128:129]
	s_or_b64 exec, exec, s[0:1]
	v_cvt_pk_bf16_f32 v100, v100, v101
	v_cvt_pk_bf16_f32 v101, v116, v117
	v_cvt_pk_bf16_f32 v102, v102, v103
	v_cvt_pk_bf16_f32 v103, v118, v119
	global_store_dwordx4 v[124:125], v[100:103], off
	v_pk_mul_f32 v[92:93], v[92:93], v[152:153] op_sel_hi:[1,0]
	s_nop 0
	v_pk_mul_f32 v[100:101], v[94:95], v[152:153] op_sel_hi:[1,0]
	v_pk_mul_f32 v[102:103], v[90:91], v[152:153] op_sel_hi:[1,0]
	v_pk_mul_f32 v[94:95], v[88:89], v[152:153] op_sel_hi:[1,0]
	s_and_saveexec_b64 s[0:1], s[4:5]
	s_xor_b64 s[0:1], exec, s[0:1]
	s_andn2_saveexec_b64 s[16:17], s[0:1]
	s_cbranch_execz .LBB0_409
	v_pk_add_f32 v[90:91], v[92:93], v[104:105]
	v_pk_add_f32 v[92:93], v[94:95], v[108:109]
	v_mul_f32_e32 v90, 0xbfb8aa3b, v90
	v_exp_f32_e32 v90, v90
	v_mul_f32_e32 v92, 0xbfb8aa3b, v92
	v_exp_f32_e32 v94, v92
	v_mul_f32_e32 v91, 0xbfb8aa3b, v91
	v_exp_f32_e32 v91, v91
	v_mul_f32_e32 v93, 0xbfb8aa3b, v93
	v_exp_f32_e32 v95, v93
	v_pk_add_f32 v[88:89], v[100:101], v[106:107]
	v_add_f32_e32 v90, 1.0, v90
	v_pk_add_f32 v[100:101], v[102:103], v[110:111]
	v_rcp_f32_e32 v92, v90
	v_add_f32_e32 v90, 1.0, v94
	v_mul_f32_e32 v88, 0xbfb8aa3b, v88
	v_rcp_f32_e32 v94, v90
	v_add_f32_e32 v90, 1.0, v91
	v_exp_f32_e32 v88, v88
	v_mul_f32_e32 v91, 0xbfb8aa3b, v100
	v_rcp_f32_e32 v93, v90
	v_add_f32_e32 v90, 1.0, v95
	v_exp_f32_e32 v91, v91
	v_mul_f32_e32 v89, 0xbfb8aa3b, v89
	v_rcp_f32_e32 v95, v90
	v_exp_f32_e32 v89, v89
	v_mul_f32_e32 v90, 0xbfb8aa3b, v101
	v_exp_f32_e32 v90, v90
	v_add_f32_e32 v88, 1.0, v88
	v_rcp_f32_e32 v100, v88
	v_add_f32_e32 v88, 1.0, v91
	v_rcp_f32_e32 v102, v88
	v_add_f32_e32 v88, 1.0, v89
	v_rcp_f32_e32 v101, v88
	v_add_f32_e32 v88, 1.0, v90
	v_rcp_f32_e32 v103, v88
; #define GAS __attribute__((address_space(1)))
; DI unsigned pk2(float lo, float hi) { f32x2 v = {lo, hi}; bf16x2_t r = __builtin_convertvector(v, bf16x2_t); return __builtin_bit_cast(unsigned, r); }
; DI float sigmoidf_(float x) { return __builtin_amdgcn_rcpf(1.f + __expf(-x)); }
;     DI bool operator()(AccT& acc, const Unit& u, int wr, int wc, int fr, int fq) const {
;     ...
;             for (int ai = 0; ai < 2; ++ai)
; #pragma unroll
;                 for (int m = 0; m < 4; ++m) {
;                     f32x4 v0 = acc[ai][bj][m][0] * rsv[ai][m], v1 = acc[ai][bj][m][1] * rsv[ai][m];
;                     if (gate) { v0 += b0; v1 += b1;
; #pragma unroll
;                         for (int e = 0; e < 4; ++e) { v0[e] = sigmoidf_(v0[e]); v1[e] = sigmoidf_(v1[e]); } }
;                     u32x4 w; w.x = pk2(v0[0], v0[1]); w.y = pk2(v0[2], v0[3]); w.z = pk2(v1[0], v1[1]); w.w = pk2(v1[2], v1[3]);
;                     if (s5c) *(GAS u32x4*)(ZS5 + ((size_t)(col >> 4) * M + (row0 + ai * HALF + m * 16)) * 16 + (col & 8)) = w;
;                     else *(GAS u32x4*)(Z + (size_t)(row0 + ai * HALF + m * 16) * ZP + col) = w;
;                 }
.LBB0_409:
	s_or_b64 exec, exec, s[16:17]
	v_add_u32_e32 v88, 0x80, v158
	v_ashrrev_i32_e32 v89, 31, v88
	s_and_saveexec_b64 s[0:1], vcc
	s_xor_b64 s[0:1], exec, s[0:1]
	v_mov_b64_e32 v[90:91], s[6:7]
	s_movk_i32 s16, 0x5a00
	v_mad_i64_i32 v[90:91], s[16:17], v88, s16, v[90:91]
	v_lshl_add_u64 v[116:117], v[184:185], 1, v[90:91]
	s_or_saveexec_b64 s[0:1], s[0:1]
	v_lshlrev_b64 v[90:91], 5, v[88:89]
	s_xor_b64 exec, exec, s[0:1]
	v_lshl_add_u64 v[116:117], v[132:133], 0, v[90:91]
	v_mov_b32_e32 v129, v185
	v_lshl_add_u64 v[116:117], v[116:117], 0, v[128:129]
	s_or_b64 exec, exec, s[0:1]
	v_cvt_pk_bf16_f32 v92, v92, v93
	v_cvt_pk_bf16_f32 v93, v100, v101
	v_cvt_pk_bf16_f32 v94, v94, v95
	v_cvt_pk_bf16_f32 v95, v102, v103
	v_mov_b32_e32 v100, v153
	global_store_dwordx4 v[116:117], v[92:95], off
	v_pk_mul_f32 v[84:85], v[84:85], v[100:101] op_sel_hi:[1,0]
	s_nop 0
	v_pk_mul_f32 v[92:93], v[86:87], v[100:101] op_sel_hi:[1,0]
	v_pk_mul_f32 v[94:95], v[82:83], v[100:101] op_sel_hi:[1,0]
	v_pk_mul_f32 v[86:87], v[80:81], v[100:101] op_sel_hi:[1,0]
	s_and_saveexec_b64 s[0:1], s[4:5]
	s_xor_b64 s[0:1], exec, s[0:1]
	s_andn2_saveexec_b64 s[16:17], s[0:1]
	s_cbranch_execz .LBB0_415
	v_pk_add_f32 v[82:83], v[84:85], v[104:105]
	v_pk_add_f32 v[84:85], v[86:87], v[108:109]
	v_mul_f32_e32 v82, 0xbfb8aa3b, v82
	v_exp_f32_e32 v82, v82
	v_mul_f32_e32 v84, 0xbfb8aa3b, v84
	v_exp_f32_e32 v86, v84
	v_mul_f32_e32 v83, 0xbfb8aa3b, v83
	v_exp_f32_e32 v83, v83
	v_mul_f32_e32 v85, 0xbfb8aa3b, v85
	v_exp_f32_e32 v87, v85
	v_pk_add_f32 v[80:81], v[92:93], v[106:107]
	v_add_f32_e32 v82, 1.0, v82
	v_pk_add_f32 v[92:93], v[94:95], v[110:111]
	v_rcp_f32_e32 v84, v82
	v_add_f32_e32 v82, 1.0, v86
	v_mul_f32_e32 v80, 0xbfb8aa3b, v80
	v_rcp_f32_e32 v86, v82
	v_add_f32_e32 v82, 1.0, v83
	v_exp_f32_e32 v80, v80
	v_mul_f32_e32 v83, 0xbfb8aa3b, v92
	v_rcp_f32_e32 v85, v82
	v_add_f32_e32 v82, 1.0, v87
	v_exp_f32_e32 v83, v83
	v_mul_f32_e32 v81, 0xbfb8aa3b, v81
	v_rcp_f32_e32 v87, v82
	v_exp_f32_e32 v81, v81
	v_mul_f32_e32 v82, 0xbfb8aa3b, v93
	v_exp_f32_e32 v82, v82
	v_add_f32_e32 v80, 1.0, v80
	v_rcp_f32_e32 v92, v80
	v_add_f32_e32 v80, 1.0, v83
	v_rcp_f32_e32 v94, v80
	v_add_f32_e32 v80, 1.0, v81
	v_rcp_f32_e32 v93, v80
	v_add_f32_e32 v80, 1.0, v82
	v_rcp_f32_e32 v95, v80
.LBB0_415:
	s_or_b64 exec, exec, s[16:17]
	v_add_u32_e32 v80, 0x90, v158
	v_ashrrev_i32_e32 v81, 31, v80
	s_and_saveexec_b64 s[0:1], vcc
	s_xor_b64 s[0:1], exec, s[0:1]
	v_mov_b64_e32 v[82:83], s[6:7]
	s_movk_i32 s16, 0x5a00
	v_mad_i64_i32 v[82:83], s[16:17], v80, s16, v[82:83]
	v_lshl_add_u64 v[100:101], v[184:185], 1, v[82:83]
	s_or_saveexec_b64 s[0:1], s[0:1]
	v_lshlrev_b64 v[82:83], 5, v[80:81]
	s_xor_b64 exec, exec, s[0:1]
	v_lshl_add_u64 v[100:101], v[132:133], 0, v[82:83]
	v_mov_b32_e32 v129, v185
	v_lshl_add_u64 v[100:101], v[100:101], 0, v[128:129]
	s_or_b64 exec, exec, s[0:1]
	v_cvt_pk_bf16_f32 v84, v84, v85
	v_cvt_pk_bf16_f32 v85, v92, v93
	v_cvt_pk_bf16_f32 v86, v86, v87
	v_cvt_pk_bf16_f32 v87, v94, v95
	global_store_dwordx4 v[100:101], v[84:87], off
	v_pk_mul_f32 v[76:77], v[76:77], v[150:151] op_sel_hi:[1,0]
	v_pk_mul_f32 v[72:73], v[72:73], v[150:151] op_sel_hi:[1,0]
	v_pk_mul_f32 v[84:85], v[78:79], v[150:151] op_sel_hi:[1,0]
	v_pk_mul_f32 v[86:87], v[74:75], v[150:151] op_sel_hi:[1,0]
	s_and_saveexec_b64 s[0:1], s[4:5]
	s_xor_b64 s[0:1], exec, s[0:1]
	s_andn2_saveexec_b64 s[16:17], s[0:1]
	s_cbranch_execz .LBB0_421
	v_pk_add_f32 v[74:75], v[84:85], v[106:107]
	v_pk_add_f32 v[78:79], v[86:87], v[110:111]
	v_mul_f32_e32 v74, 0xbfb8aa3b, v74
	v_exp_f32_e32 v74, v74
	v_mul_f32_e32 v78, 0xbfb8aa3b, v78
	v_exp_f32_e32 v78, v78
	v_pk_add_f32 v[76:77], v[76:77], v[104:105]
	v_pk_add_f32 v[72:73], v[72:73], v[108:109]
	v_add_f32_e32 v74, 1.0, v74
	v_mul_f32_e32 v75, 0xbfb8aa3b, v75
	v_mul_f32_e32 v76, 0xbfb8aa3b, v76
	v_mul_f32_e32 v72, 0xbfb8aa3b, v72
	v_mul_f32_e32 v77, 0xbfb8aa3b, v77
	v_mul_f32_e32 v73, 0xbfb8aa3b, v73
	v_rcp_f32_e32 v84, v74
	v_add_f32_e32 v74, 1.0, v78
	v_exp_f32_e32 v75, v75
	v_mul_f32_e32 v78, 0xbfb8aa3b, v79
	v_exp_f32_e32 v76, v76
	v_exp_f32_e32 v72, v72
	v_exp_f32_e32 v77, v77
	v_exp_f32_e32 v73, v73
	v_exp_f32_e32 v78, v78
	v_rcp_f32_e32 v86, v74
	v_add_f32_e32 v74, 1.0, v75
	v_add_f32_e32 v76, 1.0, v76
	v_add_f32_e32 v72, 1.0, v72
	v_add_f32_e32 v77, 1.0, v77
	v_add_f32_e32 v73, 1.0, v73
	v_rcp_f32_e32 v85, v74
	v_add_f32_e32 v74, 1.0, v78
	v_rcp_f32_e32 v76, v76
	v_rcp_f32_e32 v72, v72
	v_rcp_f32_e32 v77, v77
	v_rcp_f32_e32 v73, v73
	v_rcp_f32_e32 v87, v74
.LBB0_421:
	s_or_b64 exec, exec, s[16:17]
	v_add_u32_e32 v74, 0xa0, v158
	v_ashrrev_i32_e32 v75, 31, v74
	s_and_saveexec_b64 s[0:1], vcc
	s_xor_b64 s[0:1], exec, s[0:1]
	v_mov_b64_e32 v[78:79], s[6:7]
	s_movk_i32 s16, 0x5a00
	v_mad_i64_i32 v[78:79], s[16:17], v74, s16, v[78:79]
	v_lshl_add_u64 v[92:93], v[184:185], 1, v[78:79]
	s_or_saveexec_b64 s[0:1], s[0:1]
	v_lshlrev_b64 v[78:79], 5, v[74:75]
	s_xor_b64 exec, exec, s[0:1]
	v_lshl_add_u64 v[92:93], v[132:133], 0, v[78:79]
	v_mov_b32_e32 v129, v185
	v_lshl_add_u64 v[92:93], v[92:93], 0, v[128:129]
	s_or_b64 exec, exec, s[0:1]
	v_cvt_pk_bf16_f32 v102, v72, v73
	v_mov_b32_e32 v72, v151
	v_cvt_pk_bf16_f32 v100, v76, v77
	v_cvt_pk_bf16_f32 v101, v84, v85
	v_cvt_pk_bf16_f32 v103, v86, v87
	v_pk_mul_f32 v[70:71], v[70:71], v[72:73] op_sel_hi:[1,0]
	v_pk_mul_f32 v[68:69], v[68:69], v[72:73] op_sel_hi:[1,0]
	v_pk_mul_f32 v[66:67], v[66:67], v[72:73] op_sel_hi:[1,0]
	v_pk_mul_f32 v[64:65], v[64:65], v[72:73] op_sel_hi:[1,0]
	global_store_dwordx4 v[92:93], v[100:103], off
	s_and_saveexec_b64 s[0:1], s[4:5]
	s_xor_b64 s[0:1], exec, s[0:1]
	s_andn2_saveexec_b64 s[4:5], s[0:1]
	s_cbranch_execz .LBB0_429
	v_pk_add_f32 v[70:71], v[70:71], v[106:107]
	v_pk_add_f32 v[68:69], v[68:69], v[104:105]
	v_pk_add_f32 v[64:65], v[64:65], v[108:109]
	v_pk_add_f32 v[66:67], v[66:67], v[110:111]
	v_mul_f32_e32 v68, 0xbfb8aa3b, v68
	v_mul_f32_e32 v64, 0xbfb8aa3b, v64
	v_mul_f32_e32 v69, 0xbfb8aa3b, v69
	v_mul_f32_e32 v65, 0xbfb8aa3b, v65
	v_mul_f32_e32 v70, 0xbfb8aa3b, v70
	v_mul_f32_e32 v66, 0xbfb8aa3b, v66
	v_mul_f32_e32 v71, 0xbfb8aa3b, v71
	v_mul_f32_e32 v67, 0xbfb8aa3b, v67
	v_exp_f32_e32 v68, v68
	v_exp_f32_e32 v64, v64
	v_exp_f32_e32 v69, v69
	v_exp_f32_e32 v65, v65
	v_exp_f32_e32 v70, v70
	v_exp_f32_e32 v66, v66
	v_exp_f32_e32 v71, v71
	v_exp_f32_e32 v67, v67
	v_add_f32_e32 v68, 1.0, v68
	v_add_f32_e32 v64, 1.0, v64
	v_add_f32_e32 v69, 1.0, v69
	v_add_f32_e32 v65, 1.0, v65
	v_add_f32_e32 v70, 1.0, v70
	v_add_f32_e32 v66, 1.0, v66
	v_add_f32_e32 v71, 1.0, v71
	v_add_f32_e32 v67, 1.0, v67
	v_rcp_f32_e32 v68, v68
	v_rcp_f32_e32 v64, v64
	v_rcp_f32_e32 v69, v69
	v_rcp_f32_e32 v65, v65
	v_rcp_f32_e32 v70, v70
	v_rcp_f32_e32 v66, v66
	v_rcp_f32_e32 v71, v71
	v_rcp_f32_e32 v67, v67

; #define GAS __attribute__((address_space(1)))
; DI unsigned pk2(float lo, float hi) { f32x2 v = {lo, hi}; bf16x2_t r = __builtin_convertvector(v, bf16x2_t); return __builtin_bit_cast(unsigned, r); }
; DI float sigmoidf_(float x) { return __builtin_amdgcn_rcpf(1.f + __expf(-x)); }
;     DI bool operator()(AccT& acc, const Unit& u, int wr, int wc, int fr, int fq) const {
;     ...
;         for (int bj = 0; bj < 2; ++bj) {
;             const int col = col0 + bj * HALF; const bool gate = (col >= ZC_GATE) && (col < ZC_VRES); const bool s5c = col < S5W;
;             f32x4 b0 = {0.f, 0.f, 0.f, 0.f}, b1 = b0;
;             if (gate) { b0 = *(const GAS f32x4*)(gbias + (col - ZC_GATE)); b1 = *(const GAS f32x4*)(gbias + (col - ZC_GATE) + 4); }
; #pragma unroll
;             for (int ai = 0; ai < 2; ++ai)
; #pragma unroll
;                 for (int m = 0; m < 4; ++m) {
;                     f32x4 v0 = acc[ai][bj][m][0] * rsv[ai][m], v1 = acc[ai][bj][m][1] * rsv[ai][m];
;                     if (gate) { v0 += b0; v1 += b1;
; #pragma unroll
;                         for (int e = 0; e < 4; ++e) { v0[e] = sigmoidf_(v0[e]); v1[e] = sigmoidf_(v1[e]); } }
;                     u32x4 w; w.x = pk2(v0[0], v0[1]); w.y = pk2(v0[2], v0[3]); w.z = pk2(v1[0], v1[1]); w.w = pk2(v1[2], v1[3]);
;                     if (s5c) *(GAS u32x4*)(ZS5 + ((size_t)(col >> 4) * M + (row0 + ai * HALF + m * 16)) * 16 + (col & 8)) = w;
;                     else *(GAS u32x4*)(Z + (size_t)(row0 + ai * HALF + m * 16) * ZP + col) = w;
;                 }
.LBB0_437:
	s_or_b64 exec, exec, s[16:17]
	v_or_b32_e32 v56, 0x80, v184
	s_movk_i32 s0, 0x2ff
	v_cmp_lt_i32_e32 vcc, s0, v56
	s_and_saveexec_b64 s[0:1], vcc
	s_xor_b64 s[0:1], exec, s[0:1]
	v_mov_b64_e32 v[86:87], s[6:7]
	s_movk_i32 s16, 0x5a00
	v_mad_i64_i32 v[86:87], s[16:17], v158, s16, v[86:87]
	v_lshl_add_u64 v[86:87], v[184:185], 1, v[86:87]
	s_mov_b64 s[16:17], 0x100
	v_lshl_add_u64 v[86:87], v[86:87], 0, s[16:17]
	s_or_saveexec_b64 s[0:1], s[0:1]
	v_ashrrev_i32_e32 v56, 4, v56
	v_ashrrev_i32_e32 v57, 31, v56
	v_lshlrev_b64 v[56:57], 19, v[56:57]
	v_lshl_add_u64 v[56:57], s[10:11], 0, v[56:57]
	s_xor_b64 exec, exec, s[0:1]
	v_lshl_add_u64 v[86:87], v[56:57], 0, v[130:131]
	v_mov_b32_e32 v129, v185
	v_lshl_add_u64 v[86:87], v[86:87], 0, v[128:129]
	s_or_b64 exec, exec, s[0:1]
	v_mov_b32_e32 v156, v157
	v_cvt_pk_bf16_f32 v60, v60, v61
	v_cvt_pk_bf16_f32 v61, v62, v63
	v_cvt_pk_bf16_f32 v62, v58, v59
	v_mov_b32_e32 v58, v157
	v_mov_b32_e32 v59, v157
	v_cvt_pk_bf16_f32 v63, v84, v85
	v_pk_mul_f32 v[54:55], v[54:55], v[58:59]
	v_pk_mul_f32 v[52:53], v[52:53], v[156:157]
	v_pk_mul_f32 v[50:51], v[50:51], v[58:59]
	v_pk_mul_f32 v[48:49], v[48:49], v[156:157]
	global_store_dwordx4 v[86:87], v[60:63], off
	s_and_saveexec_b64 s[0:1], s[4:5]
	s_xor_b64 s[0:1], exec, s[0:1]
	s_andn2_saveexec_b64 s[16:17], s[0:1]
	s_cbranch_execz .LBB0_443
	v_pk_add_f32 v[54:55], v[54:55], v[70:71]
	v_pk_add_f32 v[52:53], v[52:53], v[68:69]
	v_pk_add_f32 v[48:49], v[48:49], v[64:65]
	v_pk_add_f32 v[50:51], v[50:51], v[66:67]
	v_mul_f32_e32 v52, 0xbfb8aa3b, v52
	v_mul_f32_e32 v48, 0xbfb8aa3b, v48
	v_mul_f32_e32 v53, 0xbfb8aa3b, v53
	v_mul_f32_e32 v49, 0xbfb8aa3b, v49
	v_mul_f32_e32 v54, 0xbfb8aa3b, v54
	v_mul_f32_e32 v50, 0xbfb8aa3b, v50
	v_mul_f32_e32 v55, 0xbfb8aa3b, v55
	v_mul_f32_e32 v51, 0xbfb8aa3b, v51
	v_exp_f32_e32 v52, v52
	v_exp_f32_e32 v48, v48
	v_exp_f32_e32 v53, v53
	v_exp_f32_e32 v49, v49
	v_exp_f32_e32 v54, v54
	v_exp_f32_e32 v50, v50
	v_exp_f32_e32 v55, v55
	v_exp_f32_e32 v51, v51
	v_add_f32_e32 v52, 1.0, v52
	v_add_f32_e32 v48, 1.0, v48
	v_add_f32_e32 v53, 1.0, v53
	v_add_f32_e32 v49, 1.0, v49
	v_add_f32_e32 v54, 1.0, v54
	v_add_f32_e32 v50, 1.0, v50
	v_add_f32_e32 v55, 1.0, v55
	v_add_f32_e32 v51, 1.0, v51
	v_rcp_f32_e32 v52, v52
	v_rcp_f32_e32 v48, v48
	v_rcp_f32_e32 v53, v53
	v_rcp_f32_e32 v49, v49
	v_rcp_f32_e32 v54, v54
	v_rcp_f32_e32 v50, v50
	v_rcp_f32_e32 v55, v55
	v_rcp_f32_e32 v51, v51

; #define GAS __attribute__((address_space(1)))
; DI unsigned pk2(float lo, float hi) { f32x2 v = {lo, hi}; bf16x2_t r = __builtin_convertvector(v, bf16x2_t); return __builtin_bit_cast(unsigned, r); }
; DI float sigmoidf_(float x) { return __builtin_amdgcn_rcpf(1.f + __expf(-x)); }
;     DI bool operator()(AccT& acc, const Unit& u, int wr, int wc, int fr, int fq) const {
;     ...
;             for (int ai = 0; ai < 2; ++ai)
; #pragma unroll
;                 for (int m = 0; m < 4; ++m) {
;                     f32x4 v0 = acc[ai][bj][m][0] * rsv[ai][m], v1 = acc[ai][bj][m][1] * rsv[ai][m];
;                     if (gate) { v0 += b0; v1 += b1;
; #pragma unroll
;                         for (int e = 0; e < 4; ++e) { v0[e] = sigmoidf_(v0[e]); v1[e] = sigmoidf_(v1[e]); } }
;                     u32x4 w; w.x = pk2(v0[0], v0[1]); w.y = pk2(v0[2], v0[3]); w.z = pk2(v1[0], v1[1]); w.w = pk2(v1[2], v1[3]);
;                     if (s5c) *(GAS u32x4*)(ZS5 + ((size_t)(col >> 4) * M + (row0 + ai * HALF + m * 16)) * 16 + (col & 8)) = w;
;                     else *(GAS u32x4*)(Z + (size_t)(row0 + ai * HALF + m * 16) * ZP + col) = w;
;                 }
.LBB0_447:
	s_or_b64 exec, exec, s[0:1]
	v_mov_b32_e32 v60, v154
	v_mov_b32_e32 v61, v154
	v_cvt_pk_bf16_f32 v52, v52, v53
	v_cvt_pk_bf16_f32 v53, v54, v55
	v_cvt_pk_bf16_f32 v54, v48, v49
	v_mov_b32_e32 v48, v154
	v_mov_b32_e32 v49, v154
	v_cvt_pk_bf16_f32 v55, v50, v51
	v_pk_mul_f32 v[46:47], v[46:47], v[48:49]
	v_pk_mul_f32 v[44:45], v[44:45], v[60:61]
	v_pk_mul_f32 v[42:43], v[42:43], v[48:49]
	v_pk_mul_f32 v[40:41], v[40:41], v[60:61]
	global_store_dwordx4 v[58:59], v[52:55], off
	s_and_saveexec_b64 s[0:1], s[4:5]
	s_xor_b64 s[0:1], exec, s[0:1]
	s_andn2_saveexec_b64 s[16:17], s[0:1]
	s_cbranch_execz .LBB0_449
	v_pk_add_f32 v[46:47], v[46:47], v[70:71]
	v_pk_add_f32 v[44:45], v[44:45], v[68:69]
	v_pk_add_f32 v[40:41], v[40:41], v[64:65]
	v_pk_add_f32 v[42:43], v[42:43], v[66:67]
	v_mul_f32_e32 v44, 0xbfb8aa3b, v44
	v_mul_f32_e32 v40, 0xbfb8aa3b, v40
	v_mul_f32_e32 v45, 0xbfb8aa3b, v45
	v_mul_f32_e32 v41, 0xbfb8aa3b, v41
	v_mul_f32_e32 v46, 0xbfb8aa3b, v46
	v_mul_f32_e32 v42, 0xbfb8aa3b, v42
	v_mul_f32_e32 v47, 0xbfb8aa3b, v47
	v_mul_f32_e32 v43, 0xbfb8aa3b, v43
	v_exp_f32_e32 v44, v44
	v_exp_f32_e32 v40, v40
	v_exp_f32_e32 v45, v45
	v_exp_f32_e32 v41, v41
	v_exp_f32_e32 v46, v46
	v_exp_f32_e32 v42, v42
	v_exp_f32_e32 v47, v47
	v_exp_f32_e32 v43, v43
	v_add_f32_e32 v44, 1.0, v44
	v_add_f32_e32 v40, 1.0, v40
	v_add_f32_e32 v45, 1.0, v45
	v_add_f32_e32 v41, 1.0, v41
	v_add_f32_e32 v46, 1.0, v46
	v_add_f32_e32 v42, 1.0, v42
	v_add_f32_e32 v47, 1.0, v47
	v_add_f32_e32 v43, 1.0, v43
	v_rcp_f32_e32 v44, v44
	v_rcp_f32_e32 v40, v40
	v_rcp_f32_e32 v45, v45
	v_rcp_f32_e32 v41, v41
	v_rcp_f32_e32 v46, v46
	v_rcp_f32_e32 v42, v42
	v_rcp_f32_e32 v47, v47
	v_rcp_f32_e32 v43, v43

; #define GAS __attribute__((address_space(1)))
; DI unsigned pk2(float lo, float hi) { f32x2 v = {lo, hi}; bf16x2_t r = __builtin_convertvector(v, bf16x2_t); return __builtin_bit_cast(unsigned, r); }
; DI float sigmoidf_(float x) { return __builtin_amdgcn_rcpf(1.f + __expf(-x)); }
;     DI bool operator()(AccT& acc, const Unit& u, int wr, int wc, int fr, int fq) const {
;     ...
;             for (int ai = 0; ai < 2; ++ai)
; #pragma unroll
;                 for (int m = 0; m < 4; ++m) {
;                     f32x4 v0 = acc[ai][bj][m][0] * rsv[ai][m], v1 = acc[ai][bj][m][1] * rsv[ai][m];
;                     if (gate) { v0 += b0; v1 += b1;
; #pragma unroll
;                         for (int e = 0; e < 4; ++e) { v0[e] = sigmoidf_(v0[e]); v1[e] = sigmoidf_(v1[e]); } }
;                     u32x4 w; w.x = pk2(v0[0], v0[1]); w.y = pk2(v0[2], v0[3]); w.z = pk2(v1[0], v1[1]); w.w = pk2(v1[2], v1[3]);
;                     if (s5c) *(GAS u32x4*)(ZS5 + ((size_t)(col >> 4) * M + (row0 + ai * HALF + m * 16)) * 16 + (col & 8)) = w;
;                     else *(GAS u32x4*)(Z + (size_t)(row0 + ai * HALF + m * 16) * ZP + col) = w;
;                 }
.LBB0_453:
	s_or_b64 exec, exec, s[0:1]
	v_mov_b32_e32 v154, v155
	v_cvt_pk_bf16_f32 v44, v44, v45
	v_cvt_pk_bf16_f32 v45, v46, v47
	v_cvt_pk_bf16_f32 v46, v40, v41
	v_mov_b32_e32 v40, v155
	v_mov_b32_e32 v41, v155
	v_cvt_pk_bf16_f32 v47, v42, v43
	v_pk_mul_f32 v[38:39], v[38:39], v[40:41]
	v_pk_mul_f32 v[36:37], v[36:37], v[154:155]
	v_pk_mul_f32 v[34:35], v[34:35], v[40:41]
	v_pk_mul_f32 v[32:33], v[32:33], v[154:155]
	global_store_dwordx4 v[48:49], v[44:47], off
	s_and_saveexec_b64 s[0:1], s[4:5]
	s_xor_b64 s[0:1], exec, s[0:1]
	s_andn2_saveexec_b64 s[16:17], s[0:1]
	s_cbranch_execz .LBB0_455
	v_pk_add_f32 v[38:39], v[38:39], v[70:71]
	v_pk_add_f32 v[36:37], v[36:37], v[68:69]
	v_pk_add_f32 v[32:33], v[32:33], v[64:65]
	v_pk_add_f32 v[34:35], v[34:35], v[66:67]
	v_mul_f32_e32 v36, 0xbfb8aa3b, v36
	v_mul_f32_e32 v32, 0xbfb8aa3b, v32
	v_mul_f32_e32 v37, 0xbfb8aa3b, v37
	v_mul_f32_e32 v33, 0xbfb8aa3b, v33
	v_mul_f32_e32 v38, 0xbfb8aa3b, v38
	v_mul_f32_e32 v34, 0xbfb8aa3b, v34
	v_mul_f32_e32 v39, 0xbfb8aa3b, v39
	v_mul_f32_e32 v35, 0xbfb8aa3b, v35
	v_exp_f32_e32 v36, v36
	v_exp_f32_e32 v32, v32
	v_exp_f32_e32 v37, v37
	v_exp_f32_e32 v33, v33
	v_exp_f32_e32 v38, v38
	v_exp_f32_e32 v34, v34
	v_exp_f32_e32 v39, v39
	v_exp_f32_e32 v35, v35
	v_add_f32_e32 v36, 1.0, v36
	v_add_f32_e32 v32, 1.0, v32
	v_add_f32_e32 v37, 1.0, v37
	v_add_f32_e32 v33, 1.0, v33
	v_add_f32_e32 v38, 1.0, v38
	v_add_f32_e32 v34, 1.0, v34
	v_add_f32_e32 v39, 1.0, v39
	v_add_f32_e32 v35, 1.0, v35
	v_rcp_f32_e32 v36, v36
	v_rcp_f32_e32 v32, v32
	v_rcp_f32_e32 v37, v37
	v_rcp_f32_e32 v33, v33
	v_rcp_f32_e32 v38, v38
	v_rcp_f32_e32 v34, v34
	v_rcp_f32_e32 v39, v39
	v_rcp_f32_e32 v35, v35

; #define GAS __attribute__((address_space(1)))
; DI unsigned pk2(float lo, float hi) { f32x2 v = {lo, hi}; bf16x2_t r = __builtin_convertvector(v, bf16x2_t); return __builtin_bit_cast(unsigned, r); }
; DI float sigmoidf_(float x) { return __builtin_amdgcn_rcpf(1.f + __expf(-x)); }
;     DI bool operator()(AccT& acc, const Unit& u, int wr, int wc, int fr, int fq) const {
;     ...
;             for (int ai = 0; ai < 2; ++ai)
; #pragma unroll
;                 for (int m = 0; m < 4; ++m) {
;                     f32x4 v0 = acc[ai][bj][m][0] * rsv[ai][m], v1 = acc[ai][bj][m][1] * rsv[ai][m];
;                     if (gate) { v0 += b0; v1 += b1;
; #pragma unroll
;                         for (int e = 0; e < 4; ++e) { v0[e] = sigmoidf_(v0[e]); v1[e] = sigmoidf_(v1[e]); } }
;                     u32x4 w; w.x = pk2(v0[0], v0[1]); w.y = pk2(v0[2], v0[3]); w.z = pk2(v1[0], v1[1]); w.w = pk2(v1[2], v1[3]);
;                     if (s5c) *(GAS u32x4*)(ZS5 + ((size_t)(col >> 4) * M + (row0 + ai * HALF + m * 16)) * 16 + (col & 8)) = w;
;                     else *(GAS u32x4*)(Z + (size_t)(row0 + ai * HALF + m * 16) * ZP + col) = w;
;                 }
.LBB0_459:
	s_or_b64 exec, exec, s[0:1]
	v_mov_b32_e32 v42, v152
	v_mov_b32_e32 v43, v152
	v_cvt_pk_bf16_f32 v36, v36, v37
	v_cvt_pk_bf16_f32 v37, v38, v39
	v_cvt_pk_bf16_f32 v38, v32, v33
	v_mov_b32_e32 v32, v152
	v_mov_b32_e32 v33, v152
	v_cvt_pk_bf16_f32 v39, v34, v35
	v_pk_mul_f32 v[30:31], v[30:31], v[32:33]
	v_pk_mul_f32 v[28:29], v[28:29], v[42:43]
	v_pk_mul_f32 v[26:27], v[26:27], v[32:33]
	v_pk_mul_f32 v[24:25], v[24:25], v[42:43]
	global_store_dwordx4 v[40:41], v[36:39], off
	s_and_saveexec_b64 s[0:1], s[4:5]
	s_xor_b64 s[0:1], exec, s[0:1]
	s_andn2_saveexec_b64 s[16:17], s[0:1]
	s_cbranch_execz .LBB0_461
	v_pk_add_f32 v[30:31], v[30:31], v[70:71]
	v_pk_add_f32 v[28:29], v[28:29], v[68:69]
	v_pk_add_f32 v[24:25], v[24:25], v[64:65]
	v_pk_add_f32 v[26:27], v[26:27], v[66:67]
	v_mul_f32_e32 v28, 0xbfb8aa3b, v28
	v_mul_f32_e32 v24, 0xbfb8aa3b, v24
	v_mul_f32_e32 v29, 0xbfb8aa3b, v29
	v_mul_f32_e32 v25, 0xbfb8aa3b, v25
	v_mul_f32_e32 v30, 0xbfb8aa3b, v30
	v_mul_f32_e32 v26, 0xbfb8aa3b, v26
	v_mul_f32_e32 v31, 0xbfb8aa3b, v31
	v_mul_f32_e32 v27, 0xbfb8aa3b, v27
	v_exp_f32_e32 v28, v28
	v_exp_f32_e32 v24, v24
	v_exp_f32_e32 v29, v29
	v_exp_f32_e32 v25, v25
	v_exp_f32_e32 v30, v30
	v_exp_f32_e32 v26, v26
	v_exp_f32_e32 v31, v31
	v_exp_f32_e32 v27, v27
	v_add_f32_e32 v28, 1.0, v28
	v_add_f32_e32 v24, 1.0, v24
	v_add_f32_e32 v29, 1.0, v29
	v_add_f32_e32 v25, 1.0, v25
	v_add_f32_e32 v30, 1.0, v30
	v_add_f32_e32 v26, 1.0, v26
	v_add_f32_e32 v31, 1.0, v31
	v_add_f32_e32 v27, 1.0, v27
	v_rcp_f32_e32 v28, v28
	v_rcp_f32_e32 v24, v24
	v_rcp_f32_e32 v29, v29
	v_rcp_f32_e32 v25, v25
	v_rcp_f32_e32 v30, v30
	v_rcp_f32_e32 v26, v26
	v_rcp_f32_e32 v31, v31
	v_rcp_f32_e32 v27, v27

; #define GAS __attribute__((address_space(1)))
; DI unsigned pk2(float lo, float hi) { f32x2 v = {lo, hi}; bf16x2_t r = __builtin_convertvector(v, bf16x2_t); return __builtin_bit_cast(unsigned, r); }
; DI float sigmoidf_(float x) { return __builtin_amdgcn_rcpf(1.f + __expf(-x)); }
;     DI bool operator()(AccT& acc, const Unit& u, int wr, int wc, int fr, int fq) const {
;     ...
;             for (int ai = 0; ai < 2; ++ai)
; #pragma unroll
;                 for (int m = 0; m < 4; ++m) {
;                     f32x4 v0 = acc[ai][bj][m][0] * rsv[ai][m], v1 = acc[ai][bj][m][1] * rsv[ai][m];
;                     if (gate) { v0 += b0; v1 += b1;
; #pragma unroll
;                         for (int e = 0; e < 4; ++e) { v0[e] = sigmoidf_(v0[e]); v1[e] = sigmoidf_(v1[e]); } }
;                     u32x4 w; w.x = pk2(v0[0], v0[1]); w.y = pk2(v0[2], v0[3]); w.z = pk2(v1[0], v1[1]); w.w = pk2(v1[2], v1[3]);
;                     if (s5c) *(GAS u32x4*)(ZS5 + ((size_t)(col >> 4) * M + (row0 + ai * HALF + m * 16)) * 16 + (col & 8)) = w;
;                     else *(GAS u32x4*)(Z + (size_t)(row0 + ai * HALF + m * 16) * ZP + col) = w;
;                 }
.LBB0_465:
	s_or_b64 exec, exec, s[0:1]
	v_mov_b32_e32 v152, v153
	v_cvt_pk_bf16_f32 v28, v28, v29
	v_cvt_pk_bf16_f32 v29, v30, v31
	v_cvt_pk_bf16_f32 v30, v24, v25
	v_mov_b32_e32 v24, v153
	v_mov_b32_e32 v25, v153
	v_cvt_pk_bf16_f32 v31, v26, v27
	v_pk_mul_f32 v[22:23], v[22:23], v[24:25]
	v_pk_mul_f32 v[20:21], v[20:21], v[152:153]
	v_pk_mul_f32 v[18:19], v[18:19], v[24:25]
	v_pk_mul_f32 v[16:17], v[16:17], v[152:153]
	global_store_dwordx4 v[32:33], v[28:31], off
	s_and_saveexec_b64 s[0:1], s[4:5]
	s_xor_b64 s[0:1], exec, s[0:1]
	s_andn2_saveexec_b64 s[16:17], s[0:1]
	s_cbranch_execz .LBB0_467
	v_pk_add_f32 v[22:23], v[22:23], v[70:71]
	v_pk_add_f32 v[20:21], v[20:21], v[68:69]
	v_pk_add_f32 v[16:17], v[16:17], v[64:65]
	v_pk_add_f32 v[18:19], v[18:19], v[66:67]
	v_mul_f32_e32 v20, 0xbfb8aa3b, v20
	v_mul_f32_e32 v16, 0xbfb8aa3b, v16
	v_mul_f32_e32 v21, 0xbfb8aa3b, v21
	v_mul_f32_e32 v17, 0xbfb8aa3b, v17
	v_mul_f32_e32 v22, 0xbfb8aa3b, v22
	v_mul_f32_e32 v18, 0xbfb8aa3b, v18
	v_mul_f32_e32 v23, 0xbfb8aa3b, v23
	v_mul_f32_e32 v19, 0xbfb8aa3b, v19
	v_exp_f32_e32 v20, v20
	v_exp_f32_e32 v16, v16
	v_exp_f32_e32 v21, v21
	v_exp_f32_e32 v17, v17
	v_exp_f32_e32 v22, v22
	v_exp_f32_e32 v18, v18
	v_exp_f32_e32 v23, v23
	v_exp_f32_e32 v19, v19
	v_add_f32_e32 v20, 1.0, v20
	v_add_f32_e32 v16, 1.0, v16
	v_add_f32_e32 v21, 1.0, v21
	v_add_f32_e32 v17, 1.0, v17
	v_add_f32_e32 v22, 1.0, v22
	v_add_f32_e32 v18, 1.0, v18
	v_add_f32_e32 v23, 1.0, v23
	v_add_f32_e32 v19, 1.0, v19
	v_rcp_f32_e32 v20, v20
	v_rcp_f32_e32 v16, v16
	v_rcp_f32_e32 v21, v21
	v_rcp_f32_e32 v17, v17
	v_rcp_f32_e32 v22, v22
	v_rcp_f32_e32 v18, v18
	v_rcp_f32_e32 v23, v23
	v_rcp_f32_e32 v19, v19

; #define GAS __attribute__((address_space(1)))
; DI unsigned pk2(float lo, float hi) { f32x2 v = {lo, hi}; bf16x2_t r = __builtin_convertvector(v, bf16x2_t); return __builtin_bit_cast(unsigned, r); }
; DI float sigmoidf_(float x) { return __builtin_amdgcn_rcpf(1.f + __expf(-x)); }
;     DI bool operator()(AccT& acc, const Unit& u, int wr, int wc, int fr, int fq) const {
;     ...
;             for (int ai = 0; ai < 2; ++ai)
; #pragma unroll
;                 for (int m = 0; m < 4; ++m) {
;                     f32x4 v0 = acc[ai][bj][m][0] * rsv[ai][m], v1 = acc[ai][bj][m][1] * rsv[ai][m];
;                     if (gate) { v0 += b0; v1 += b1;
; #pragma unroll
;                         for (int e = 0; e < 4; ++e) { v0[e] = sigmoidf_(v0[e]); v1[e] = sigmoidf_(v1[e]); } }
;                     u32x4 w; w.x = pk2(v0[0], v0[1]); w.y = pk2(v0[2], v0[3]); w.z = pk2(v1[0], v1[1]); w.w = pk2(v1[2], v1[3]);
;                     if (s5c) *(GAS u32x4*)(ZS5 + ((size_t)(col >> 4) * M + (row0 + ai * HALF + m * 16)) * 16 + (col & 8)) = w;
;                     else *(GAS u32x4*)(Z + (size_t)(row0 + ai * HALF + m * 16) * ZP + col) = w;
;                 }
.LBB0_471:
	s_or_b64 exec, exec, s[0:1]
	v_mov_b32_e32 v26, v150
	v_mov_b32_e32 v27, v150
	v_cvt_pk_bf16_f32 v20, v20, v21
	v_cvt_pk_bf16_f32 v21, v22, v23
	v_cvt_pk_bf16_f32 v22, v16, v17
	v_mov_b32_e32 v16, v150
	v_mov_b32_e32 v17, v150
	v_cvt_pk_bf16_f32 v23, v18, v19
	v_pk_mul_f32 v[14:15], v[14:15], v[16:17]
	v_pk_mul_f32 v[12:13], v[12:13], v[26:27]
	v_pk_mul_f32 v[10:11], v[10:11], v[16:17]
	v_pk_mul_f32 v[8:9], v[8:9], v[26:27]
	global_store_dwordx4 v[24:25], v[20:23], off
	s_and_saveexec_b64 s[0:1], s[4:5]
	s_xor_b64 s[0:1], exec, s[0:1]
	s_andn2_saveexec_b64 s[16:17], s[0:1]
	s_cbranch_execz .LBB0_473
	v_pk_add_f32 v[14:15], v[14:15], v[70:71]
	v_pk_add_f32 v[12:13], v[12:13], v[68:69]
	v_pk_add_f32 v[8:9], v[8:9], v[64:65]
	v_pk_add_f32 v[10:11], v[10:11], v[66:67]
	v_mul_f32_e32 v12, 0xbfb8aa3b, v12
	v_mul_f32_e32 v8, 0xbfb8aa3b, v8
	v_mul_f32_e32 v13, 0xbfb8aa3b, v13
	v_mul_f32_e32 v9, 0xbfb8aa3b, v9
	v_mul_f32_e32 v14, 0xbfb8aa3b, v14
	v_mul_f32_e32 v10, 0xbfb8aa3b, v10
	v_mul_f32_e32 v15, 0xbfb8aa3b, v15
	v_mul_f32_e32 v11, 0xbfb8aa3b, v11
	v_exp_f32_e32 v12, v12
	v_exp_f32_e32 v8, v8
	v_exp_f32_e32 v13, v13
	v_exp_f32_e32 v9, v9
	v_exp_f32_e32 v14, v14
	v_exp_f32_e32 v10, v10
	v_exp_f32_e32 v15, v15
	v_exp_f32_e32 v11, v11
	v_add_f32_e32 v12, 1.0, v12
	v_add_f32_e32 v8, 1.0, v8
	v_add_f32_e32 v13, 1.0, v13
	v_add_f32_e32 v9, 1.0, v9
	v_add_f32_e32 v14, 1.0, v14
	v_add_f32_e32 v10, 1.0, v10
	v_add_f32_e32 v15, 1.0, v15
	v_add_f32_e32 v11, 1.0, v11
	v_rcp_f32_e32 v12, v12
	v_rcp_f32_e32 v8, v8
	v_rcp_f32_e32 v13, v13
	v_rcp_f32_e32 v9, v9
	v_rcp_f32_e32 v14, v14
	v_rcp_f32_e32 v10, v10
	v_rcp_f32_e32 v15, v15
	v_rcp_f32_e32 v11, v11

; DI float sigmoidf_(float x) { return __builtin_amdgcn_rcpf(1.f + __expf(-x)); }
;     DI bool operator()(AccT& acc, const Unit& u, int wr, int wc, int fr, int fq) const {
;     ...
;                     if (gate) { v0 += b0; v1 += b1;
; #pragma unroll
;                         for (int e = 0; e < 4; ++e) { v0[e] = sigmoidf_(v0[e]); v1[e] = sigmoidf_(v1[e]); } }
.LBB0_480:
	v_pk_add_f32 v[6:7], v[6:7], v[70:71]
	v_pk_add_f32 v[4:5], v[4:5], v[68:69]
	v_pk_add_f32 v[0:1], v[0:1], v[64:65]
	v_pk_add_f32 v[2:3], v[2:3], v[66:67]
	v_mul_f32_e32 v4, 0xbfb8aa3b, v4
	v_mul_f32_e32 v0, 0xbfb8aa3b, v0
	v_mul_f32_e32 v5, 0xbfb8aa3b, v5
	v_mul_f32_e32 v1, 0xbfb8aa3b, v1
	v_mul_f32_e32 v6, 0xbfb8aa3b, v6
	v_mul_f32_e32 v2, 0xbfb8aa3b, v2
	v_mul_f32_e32 v7, 0xbfb8aa3b, v7
	v_mul_f32_e32 v3, 0xbfb8aa3b, v3
	v_exp_f32_e32 v4, v4
	v_exp_f32_e32 v0, v0
	v_exp_f32_e32 v5, v5
	v_exp_f32_e32 v1, v1
	v_exp_f32_e32 v6, v6
	v_exp_f32_e32 v2, v2
	v_exp_f32_e32 v7, v7
	v_exp_f32_e32 v3, v3
	v_add_f32_e32 v4, 1.0, v4
	v_add_f32_e32 v0, 1.0, v0
	v_add_f32_e32 v5, 1.0, v5
	v_add_f32_e32 v1, 1.0, v1
	v_add_f32_e32 v6, 1.0, v6
	v_add_f32_e32 v2, 1.0, v2
	v_add_f32_e32 v7, 1.0, v7
	v_add_f32_e32 v3, 1.0, v3
	v_rcp_f32_e32 v4, v4
	v_rcp_f32_e32 v0, v0
	v_rcp_f32_e32 v5, v5
	v_rcp_f32_e32 v1, v1
	v_rcp_f32_e32 v6, v6
	v_rcp_f32_e32 v2, v2
	v_rcp_f32_e32 v7, v7
	v_rcp_f32_e32 v3, v3
